# k16
# speedup vs baseline: 1.1238x; 1.0034x over previous
.Lat_kb:
	s_add_u32 s88, s86, 1
	s_sub_u32 s89, s17, 1
	s_min_u32 s88, s88, s89
	s_lshl_b32 s89, s88, 17
	s_add_u32 s90, s78, s89
	s_addc_u32 s91, s79, 0
	global_load_dwordx4 a[224:227], v8, s[90:91]
	global_load_dwordx4 a[228:231], v9, s[90:91]
	global_load_dwordx4 a[232:235], v10, s[90:91]
	global_load_dwordx4 a[236:239], v11, s[90:91]
	s_lshl_b32 s89, s88, 7
	s_add_u32 s90, s80, s89
	s_addc_u32 s91, s81, 0
	global_load_dwordx4 a[240:243], v12, s[90:91]
	global_load_dwordx4 a[244:247], v13, s[90:91]
	global_load_dwordx4 a[248:251], v14, s[90:91]
	global_load_dwordx4 a[252:255], v15, s[90:91]
	s_add_u32 s88, s84, 31
	s_cmp_gt_u32 s85, s88
	s_cbranch_scc1 .Lat_skip
	v_add_u32_e32 v6, s87, v4
	v_add_u32_e32 v7, s87, v5
	ds_read_b128 a[32:35], v6 offset:0
	ds_read_b128 a[36:39], v6 offset:32
	ds_read_b128 a[40:43], v6 offset:64
	ds_read_b128 a[44:47], v6 offset:96
	ds_read_b128 a[48:51], v6 offset:8704
	ds_read_b128 a[52:55], v6 offset:8736
	ds_read_b128 a[56:59], v6 offset:8768
	ds_read_b128 a[60:63], v6 offset:8800
	ds_read_b128 a[64:67], v6 offset:128
	ds_read_b128 a[68:71], v6 offset:160
	ds_read_b128 a[72:75], v6 offset:192
	ds_read_b128 a[76:79], v6 offset:224
	ds_read_b128 a[80:83], v6 offset:8832
	ds_read_b128 a[84:87], v6 offset:8864
	ds_read_b128 a[88:91], v6 offset:8896
	ds_read_b128 a[92:95], v6 offset:8928
	s_add_u32 s88, s85, 63
	s_cmp_gt_u32 s88, s84
	s_cbranch_scc1 .Lat_diag
	s_waitcnt lgkmcnt(15)
	v_mfma_f32_32x32x16_bf16 v[192:207], a[32:35], a[0:3], 0
	s_waitcnt lgkmcnt(11)
	v_mfma_f32_32x32x16_bf16 v[208:223], a[48:51], a[0:3], 0
	s_waitcnt lgkmcnt(14)
	v_mfma_f32_32x32x16_bf16 v[192:207], a[36:39], a[4:7], v[192:207]
	s_waitcnt lgkmcnt(10)
	v_mfma_f32_32x32x16_bf16 v[208:223], a[52:55], a[4:7], v[208:223]
	s_waitcnt lgkmcnt(13)
	v_mfma_f32_32x32x16_bf16 v[192:207], a[40:43], a[8:11], v[192:207]
	s_waitcnt lgkmcnt(9)
	v_mfma_f32_32x32x16_bf16 v[208:223], a[56:59], a[8:11], v[208:223]
	s_waitcnt lgkmcnt(12)
	v_mfma_f32_32x32x16_bf16 v[192:207], a[44:47], a[12:15], v[192:207]
	s_waitcnt lgkmcnt(8)
	v_mfma_f32_32x32x16_bf16 v[208:223], a[60:63], a[12:15], v[208:223]
	s_waitcnt lgkmcnt(7)
	v_mfma_f32_32x32x16_bf16 v[32:47], a[64:67], a[16:19], 0
	s_waitcnt lgkmcnt(3)
	v_mfma_f32_32x32x16_bf16 v[48:63], a[80:83], a[16:19], 0
	s_waitcnt lgkmcnt(6)
	v_mfma_f32_32x32x16_bf16 v[32:47], a[68:71], a[20:23], v[32:47]
	s_waitcnt lgkmcnt(2)
	v_mfma_f32_32x32x16_bf16 v[48:63], a[84:87], a[20:23], v[48:63]
	ds_read2_b64 a[96:99], v7 offset0:0 offset1:2
	ds_read2_b64 a[100:103], v7 offset0:4 offset1:6
	ds_read2_b64 a[128:131], v7 offset0:8 offset1:10
	ds_read2_b64 a[132:135], v7 offset0:12 offset1:14
	v_add_u32_e32 v28, 0x1200, v7
	ds_read2_b64 a[104:107], v28 offset0:0 offset1:2
	ds_read2_b64 a[108:111], v28 offset0:4 offset1:6
	ds_read2_b64 a[136:139], v28 offset0:8 offset1:10
	ds_read2_b64 a[140:143], v28 offset0:12 offset1:14
	v_add_u32_e32 v28, 0x2400, v7
	ds_read2_b64 a[112:115], v28 offset0:0 offset1:2
	ds_read2_b64 a[116:119], v28 offset0:4 offset1:6
	ds_read2_b64 a[144:147], v28 offset0:8 offset1:10
	ds_read2_b64 a[148:151], v28 offset0:12 offset1:14
	v_add_u32_e32 v28, 0x3600, v7
	ds_read2_b64 a[120:123], v28 offset0:0 offset1:2
	ds_read2_b64 a[124:127], v28 offset0:4 offset1:6
	ds_read2_b64 a[152:155], v28 offset0:8 offset1:10
	ds_read2_b64 a[156:159], v28 offset0:12 offset1:14
	s_waitcnt lgkmcnt(15)
	v_mfma_f32_32x32x16_bf16 v[32:47], a[72:75], a[24:27], v[32:47]
	v_max3_f32 v224, v192, v193, v194
	v_max3_f32 v224, v224, v195, v196
	v_max3_f32 v224, v224, v197, v198
	v_max3_f32 v224, v224, v199, v200
	v_max3_f32 v224, v224, v201, v202
	v_max3_f32 v224, v224, v203, v204
	v_max3_f32 v224, v224, v205, v206
	v_max3_f32 v224, v224, v207, v208
	s_waitcnt lgkmcnt(15)
	v_mfma_f32_32x32x16_bf16 v[48:63], a[88:91], a[24:27], v[48:63]
	v_max3_f32 v224, v224, v209, v210
	v_max3_f32 v224, v224, v211, v212
	v_max3_f32 v224, v224, v213, v214
	v_max3_f32 v224, v224, v215, v216
	v_max3_f32 v224, v224, v217, v218
	v_max3_f32 v224, v224, v219, v220
	v_max3_f32 v224, v224, v221, v222
	v_max_f32_e32 v224, v224, v223
	s_waitcnt lgkmcnt(15)
	v_mfma_f32_32x32x16_bf16 v[32:47], a[76:79], a[28:31], v[32:47]
	ds_bpermute_b32 v225, v26, v224
	s_waitcnt lgkmcnt(0)
	v_max3_f32 v226, v224, v225, v20
	v_sub_f32_e32 v228, v20, v226
	v_exp_f32_e32 v228, v228
	v_mov_b32_e32 v20, v226
	v_sub_f32_e32 v192, v192, v226
	v_sub_f32_e32 v193, v193, v226
	s_waitcnt lgkmcnt(15)
	v_mfma_f32_32x32x16_bf16 v[48:63], a[92:95], a[28:31], v[48:63]
	v_sub_f32_e32 v194, v194, v226
	v_sub_f32_e32 v195, v195, v226
	v_sub_f32_e32 v196, v196, v226
	v_sub_f32_e32 v197, v197, v226
	v_sub_f32_e32 v198, v198, v226
	v_sub_f32_e32 v199, v199, v226
	v_sub_f32_e32 v200, v200, v226
	v_sub_f32_e32 v201, v201, v226
	v_sub_f32_e32 v202, v202, v226
	v_sub_f32_e32 v203, v203, v226
	v_sub_f32_e32 v204, v204, v226
	v_sub_f32_e32 v205, v205, v226
	v_sub_f32_e32 v206, v206, v226
	v_sub_f32_e32 v207, v207, v226
	v_sub_f32_e32 v208, v208, v226
	v_sub_f32_e32 v209, v209, v226
	v_sub_f32_e32 v210, v210, v226
	v_sub_f32_e32 v211, v211, v226
	v_sub_f32_e32 v212, v212, v226
	v_sub_f32_e32 v213, v213, v226
	v_sub_f32_e32 v214, v214, v226
	v_sub_f32_e32 v215, v215, v226
	v_sub_f32_e32 v216, v216, v226
	v_sub_f32_e32 v217, v217, v226
	v_sub_f32_e32 v218, v218, v226
	v_sub_f32_e32 v219, v219, v226
	v_sub_f32_e32 v220, v220, v226
	v_sub_f32_e32 v221, v221, v226
	v_sub_f32_e32 v222, v222, v226
	v_sub_f32_e32 v223, v223, v226
	v_exp_f32_e32 v192, v192
	v_exp_f32_e32 v193, v193
	v_exp_f32_e32 v194, v194
	v_exp_f32_e32 v195, v195
	v_exp_f32_e32 v196, v196
	v_exp_f32_e32 v197, v197
	v_exp_f32_e32 v198, v198
	v_exp_f32_e32 v199, v199
	v_exp_f32_e32 v200, v200
	v_exp_f32_e32 v201, v201
	v_exp_f32_e32 v202, v202
	v_exp_f32_e32 v203, v203
	v_exp_f32_e32 v204, v204
	v_exp_f32_e32 v205, v205
	v_exp_f32_e32 v206, v206
	v_exp_f32_e32 v207, v207
	v_exp_f32_e32 v208, v208
	v_exp_f32_e32 v209, v209
	v_exp_f32_e32 v210, v210
	v_exp_f32_e32 v211, v211
	v_exp_f32_e32 v212, v212
	v_exp_f32_e32 v213, v213
	v_exp_f32_e32 v214, v214
	v_exp_f32_e32 v215, v215
	v_exp_f32_e32 v216, v216
	v_exp_f32_e32 v217, v217
	v_exp_f32_e32 v218, v218
	v_exp_f32_e32 v219, v219
	v_exp_f32_e32 v220, v220
	v_exp_f32_e32 v221, v221
	v_exp_f32_e32 v222, v222
	v_exp_f32_e32 v223, v223
	v_mul_f32_e32 v22, v22, v228
	v_add_f32_e32 v230, v192, v193
	v_add_f32_e32 v230, v230, v194
	v_add_f32_e32 v230, v230, v195
	v_add_f32_e32 v230, v230, v196
	v_add_f32_e32 v230, v230, v197
	v_add_f32_e32 v230, v230, v198
	v_add_f32_e32 v230, v230, v199
	v_add_f32_e32 v230, v230, v200
	v_add_f32_e32 v230, v230, v201
	v_add_f32_e32 v230, v230, v202
	v_add_f32_e32 v230, v230, v203
	v_add_f32_e32 v230, v230, v204
	v_add_f32_e32 v230, v230, v205
	v_add_f32_e32 v230, v230, v206
	v_add_f32_e32 v230, v230, v207
	v_add_f32_e32 v230, v230, v208
	v_add_f32_e32 v230, v230, v209
	v_add_f32_e32 v230, v230, v210
	v_add_f32_e32 v230, v230, v211
	v_add_f32_e32 v230, v230, v212
	v_add_f32_e32 v230, v230, v213
	v_add_f32_e32 v230, v230, v214
	v_add_f32_e32 v230, v230, v215
	v_add_f32_e32 v230, v230, v216
	v_add_f32_e32 v230, v230, v217
	v_add_f32_e32 v230, v230, v218
	v_add_f32_e32 v230, v230, v219
	v_add_f32_e32 v230, v230, v220
	v_add_f32_e32 v230, v230, v221
	v_add_f32_e32 v230, v230, v222
	v_add_f32_e32 v230, v230, v223
	v_add_f32_e32 v22, v22, v230
	v_pk_mul_f32 v[64:65], v[64:65], v[228:229] op_sel_hi:[1,0]
	v_pk_mul_f32 v[66:67], v[66:67], v[228:229] op_sel_hi:[1,0]
	v_pk_mul_f32 v[68:69], v[68:69], v[228:229] op_sel_hi:[1,0]
	v_pk_mul_f32 v[70:71], v[70:71], v[228:229] op_sel_hi:[1,0]
	v_pk_mul_f32 v[72:73], v[72:73], v[228:229] op_sel_hi:[1,0]
	v_pk_mul_f32 v[74:75], v[74:75], v[228:229] op_sel_hi:[1,0]
	v_pk_mul_f32 v[76:77], v[76:77], v[228:229] op_sel_hi:[1,0]
	v_pk_mul_f32 v[78:79], v[78:79], v[228:229] op_sel_hi:[1,0]
	v_pk_mul_f32 v[80:81], v[80:81], v[228:229] op_sel_hi:[1,0]
	v_pk_mul_f32 v[82:83], v[82:83], v[228:229] op_sel_hi:[1,0]
	v_pk_mul_f32 v[84:85], v[84:85], v[228:229] op_sel_hi:[1,0]
	v_pk_mul_f32 v[86:87], v[86:87], v[228:229] op_sel_hi:[1,0]
	v_pk_mul_f32 v[88:89], v[88:89], v[228:229] op_sel_hi:[1,0]
	v_pk_mul_f32 v[90:91], v[90:91], v[228:229] op_sel_hi:[1,0]
	v_pk_mul_f32 v[92:93], v[92:93], v[228:229] op_sel_hi:[1,0]
	v_pk_mul_f32 v[94:95], v[94:95], v[228:229] op_sel_hi:[1,0]
	v_pk_mul_f32 v[96:97], v[96:97], v[228:229] op_sel_hi:[1,0]
	v_pk_mul_f32 v[98:99], v[98:99], v[228:229] op_sel_hi:[1,0]
	v_pk_mul_f32 v[100:101], v[100:101], v[228:229] op_sel_hi:[1,0]
	v_pk_mul_f32 v[102:103], v[102:103], v[228:229] op_sel_hi:[1,0]
	v_pk_mul_f32 v[104:105], v[104:105], v[228:229] op_sel_hi:[1,0]
	v_pk_mul_f32 v[106:107], v[106:107], v[228:229] op_sel_hi:[1,0]
	v_pk_mul_f32 v[108:109], v[108:109], v[228:229] op_sel_hi:[1,0]
	v_pk_mul_f32 v[110:111], v[110:111], v[228:229] op_sel_hi:[1,0]
	v_pk_mul_f32 v[112:113], v[112:113], v[228:229] op_sel_hi:[1,0]
	v_pk_mul_f32 v[114:115], v[114:115], v[228:229] op_sel_hi:[1,0]
	v_pk_mul_f32 v[116:117], v[116:117], v[228:229] op_sel_hi:[1,0]
	v_pk_mul_f32 v[118:119], v[118:119], v[228:229] op_sel_hi:[1,0]
	v_pk_mul_f32 v[120:121], v[120:121], v[228:229] op_sel_hi:[1,0]
	v_pk_mul_f32 v[122:123], v[122:123], v[228:229] op_sel_hi:[1,0]
	v_pk_mul_f32 v[124:125], v[124:125], v[228:229] op_sel_hi:[1,0]
	v_pk_mul_f32 v[126:127], v[126:127], v[228:229] op_sel_hi:[1,0]
	v_cvt_pk_bf16_f32 v192, v192, v193
	v_cvt_pk_bf16_f32 v193, v194, v195
	v_cvt_pk_bf16_f32 v194, v196, v197
	v_cvt_pk_bf16_f32 v195, v198, v199
	v_cvt_pk_bf16_f32 v196, v200, v201
	v_cvt_pk_bf16_f32 v197, v202, v203
	v_cvt_pk_bf16_f32 v198, v204, v205
	v_cvt_pk_bf16_f32 v199, v206, v207
	v_cvt_pk_bf16_f32 v208, v208, v209
	v_cvt_pk_bf16_f32 v209, v210, v211
	v_cvt_pk_bf16_f32 v210, v212, v213
	v_cvt_pk_bf16_f32 v211, v214, v215
	v_cvt_pk_bf16_f32 v212, v216, v217
	v_cvt_pk_bf16_f32 v213, v218, v219
	v_cvt_pk_bf16_f32 v214, v220, v221
	v_cvt_pk_bf16_f32 v215, v222, v223
	s_nop 1
	v_mfma_f32_32x32x16_bf16 v[64:79], a[96:99], v[192:195], v[64:79]
	v_max3_f32 v232, v32, v33, v34
	v_max3_f32 v232, v232, v35, v36
	v_max3_f32 v232, v232, v37, v38
	v_max3_f32 v232, v232, v39, v40
	v_max3_f32 v232, v232, v41, v42
	v_max3_f32 v232, v232, v43, v44
	v_max3_f32 v232, v232, v45, v46
	v_max3_f32 v232, v232, v47, v48
	v_mfma_f32_32x32x16_bf16 v[64:79], a[100:103], v[196:199], v[64:79]
	v_max3_f32 v232, v232, v49, v50
	v_max3_f32 v232, v232, v51, v52
	v_max3_f32 v232, v232, v53, v54
	v_max3_f32 v232, v232, v55, v56
	v_max3_f32 v232, v232, v57, v58
	v_max3_f32 v232, v232, v59, v60
	v_max3_f32 v232, v232, v61, v62
	v_max_f32_e32 v232, v232, v63
	v_mfma_f32_32x32x16_bf16 v[80:95], a[104:107], v[192:195], v[80:95]
	ds_bpermute_b32 v233, v26, v232
	s_waitcnt lgkmcnt(0)
	v_max3_f32 v234, v232, v233, v21
	v_sub_f32_e32 v236, v21, v234
	v_exp_f32_e32 v236, v236
	v_mov_b32_e32 v21, v234
	v_sub_f32_e32 v32, v32, v234
	v_sub_f32_e32 v33, v33, v234
	v_mfma_f32_32x32x16_bf16 v[80:95], a[108:111], v[196:199], v[80:95]
	v_sub_f32_e32 v34, v34, v234
	v_sub_f32_e32 v35, v35, v234
	v_sub_f32_e32 v36, v36, v234
	v_sub_f32_e32 v37, v37, v234
	v_sub_f32_e32 v38, v38, v234
	v_sub_f32_e32 v39, v39, v234
	v_sub_f32_e32 v40, v40, v234
	v_sub_f32_e32 v41, v41, v234
	v_mfma_f32_32x32x16_bf16 v[96:111], a[112:115], v[192:195], v[96:111]
	v_sub_f32_e32 v42, v42, v234
	v_sub_f32_e32 v43, v43, v234
	v_sub_f32_e32 v44, v44, v234
	v_sub_f32_e32 v45, v45, v234
	v_sub_f32_e32 v46, v46, v234
	v_sub_f32_e32 v47, v47, v234
	v_sub_f32_e32 v48, v48, v234
	v_sub_f32_e32 v49, v49, v234
	v_mfma_f32_32x32x16_bf16 v[96:111], a[116:119], v[196:199], v[96:111]
	v_sub_f32_e32 v50, v50, v234
	v_sub_f32_e32 v51, v51, v234
	v_sub_f32_e32 v52, v52, v234
	v_sub_f32_e32 v53, v53, v234
	v_sub_f32_e32 v54, v54, v234
	v_sub_f32_e32 v55, v55, v234
	v_sub_f32_e32 v56, v56, v234
	v_sub_f32_e32 v57, v57, v234
	v_mfma_f32_32x32x16_bf16 v[112:127], a[120:123], v[192:195], v[112:127]
	v_sub_f32_e32 v58, v58, v234
	v_sub_f32_e32 v59, v59, v234
	v_sub_f32_e32 v60, v60, v234
	v_sub_f32_e32 v61, v61, v234
	v_sub_f32_e32 v62, v62, v234
	v_sub_f32_e32 v63, v63, v234
	v_exp_f32_e32 v32, v32
	v_exp_f32_e32 v33, v33
	v_mfma_f32_32x32x16_bf16 v[112:127], a[124:127], v[196:199], v[112:127]
	v_exp_f32_e32 v34, v34
	v_exp_f32_e32 v35, v35
	v_exp_f32_e32 v36, v36
	v_exp_f32_e32 v37, v37
	v_exp_f32_e32 v38, v38
	v_exp_f32_e32 v39, v39
	v_exp_f32_e32 v40, v40
	v_exp_f32_e32 v41, v41
	v_mfma_f32_32x32x16_bf16 v[64:79], a[128:131], v[208:211], v[64:79]
	v_exp_f32_e32 v42, v42
	v_exp_f32_e32 v43, v43
	v_exp_f32_e32 v44, v44
	v_exp_f32_e32 v45, v45
	v_exp_f32_e32 v46, v46
	v_exp_f32_e32 v47, v47
	v_exp_f32_e32 v48, v48
	v_exp_f32_e32 v49, v49
	v_mfma_f32_32x32x16_bf16 v[64:79], a[132:135], v[212:215], v[64:79]
	v_exp_f32_e32 v50, v50
	v_exp_f32_e32 v51, v51
	v_exp_f32_e32 v52, v52
	v_exp_f32_e32 v53, v53
	v_exp_f32_e32 v54, v54
	v_exp_f32_e32 v55, v55
	v_exp_f32_e32 v56, v56
	v_exp_f32_e32 v57, v57
	v_mfma_f32_32x32x16_bf16 v[80:95], a[136:139], v[208:211], v[80:95]
	v_exp_f32_e32 v58, v58
	v_exp_f32_e32 v59, v59
	v_exp_f32_e32 v60, v60
	v_exp_f32_e32 v61, v61
	v_exp_f32_e32 v62, v62
	v_exp_f32_e32 v63, v63
	v_mul_f32_e32 v23, v23, v236
	v_add_f32_e32 v238, v32, v33
	v_mfma_f32_32x32x16_bf16 v[80:95], a[140:143], v[212:215], v[80:95]
	v_add_f32_e32 v238, v238, v34
	v_add_f32_e32 v238, v238, v35
	v_add_f32_e32 v238, v238, v36
	v_add_f32_e32 v238, v238, v37
	v_add_f32_e32 v238, v238, v38
	v_add_f32_e32 v238, v238, v39
	v_add_f32_e32 v238, v238, v40
	v_add_f32_e32 v238, v238, v41
	v_mfma_f32_32x32x16_bf16 v[96:111], a[144:147], v[208:211], v[96:111]
	v_add_f32_e32 v238, v238, v42
	v_add_f32_e32 v238, v238, v43
	v_add_f32_e32 v238, v238, v44
	v_add_f32_e32 v238, v238, v45
	v_add_f32_e32 v238, v238, v46
	v_add_f32_e32 v238, v238, v47
	v_add_f32_e32 v238, v238, v48
	v_add_f32_e32 v238, v238, v49
	v_mfma_f32_32x32x16_bf16 v[96:111], a[148:151], v[212:215], v[96:111]
	v_add_f32_e32 v238, v238, v50
	v_add_f32_e32 v238, v238, v51
	v_add_f32_e32 v238, v238, v52
	v_add_f32_e32 v238, v238, v53
	v_add_f32_e32 v238, v238, v54
	v_add_f32_e32 v238, v238, v55
	v_add_f32_e32 v238, v238, v56
	v_add_f32_e32 v238, v238, v57
	v_mfma_f32_32x32x16_bf16 v[112:127], a[152:155], v[208:211], v[112:127]
	v_add_f32_e32 v238, v238, v58
	v_add_f32_e32 v238, v238, v59
	v_add_f32_e32 v238, v238, v60
	v_add_f32_e32 v238, v238, v61
	v_add_f32_e32 v238, v238, v62
	v_add_f32_e32 v238, v238, v63
	v_add_f32_e32 v23, v23, v238
	v_pk_mul_f32 v[128:129], v[128:129], v[236:237] op_sel_hi:[1,0]
	v_mfma_f32_32x32x16_bf16 v[112:127], a[156:159], v[212:215], v[112:127]
	v_pk_mul_f32 v[130:131], v[130:131], v[236:237] op_sel_hi:[1,0]
	v_pk_mul_f32 v[132:133], v[132:133], v[236:237] op_sel_hi:[1,0]
	v_pk_mul_f32 v[134:135], v[134:135], v[236:237] op_sel_hi:[1,0]
	v_pk_mul_f32 v[136:137], v[136:137], v[236:237] op_sel_hi:[1,0]
	v_pk_mul_f32 v[138:139], v[138:139], v[236:237] op_sel_hi:[1,0]
	v_pk_mul_f32 v[140:141], v[140:141], v[236:237] op_sel_hi:[1,0]
	v_pk_mul_f32 v[142:143], v[142:143], v[236:237] op_sel_hi:[1,0]
	v_pk_mul_f32 v[144:145], v[144:145], v[236:237] op_sel_hi:[1,0]
	v_pk_mul_f32 v[146:147], v[146:147], v[236:237] op_sel_hi:[1,0]
	v_pk_mul_f32 v[148:149], v[148:149], v[236:237] op_sel_hi:[1,0]
	v_pk_mul_f32 v[150:151], v[150:151], v[236:237] op_sel_hi:[1,0]
	v_pk_mul_f32 v[152:153], v[152:153], v[236:237] op_sel_hi:[1,0]
	v_pk_mul_f32 v[154:155], v[154:155], v[236:237] op_sel_hi:[1,0]
	v_pk_mul_f32 v[156:157], v[156:157], v[236:237] op_sel_hi:[1,0]
	v_pk_mul_f32 v[158:159], v[158:159], v[236:237] op_sel_hi:[1,0]
	v_pk_mul_f32 v[160:161], v[160:161], v[236:237] op_sel_hi:[1,0]
	v_pk_mul_f32 v[162:163], v[162:163], v[236:237] op_sel_hi:[1,0]
	v_pk_mul_f32 v[164:165], v[164:165], v[236:237] op_sel_hi:[1,0]
	v_pk_mul_f32 v[166:167], v[166:167], v[236:237] op_sel_hi:[1,0]
	v_pk_mul_f32 v[168:169], v[168:169], v[236:237] op_sel_hi:[1,0]
	v_pk_mul_f32 v[170:171], v[170:171], v[236:237] op_sel_hi:[1,0]
	v_pk_mul_f32 v[172:173], v[172:173], v[236:237] op_sel_hi:[1,0]
	v_pk_mul_f32 v[174:175], v[174:175], v[236:237] op_sel_hi:[1,0]
	v_pk_mul_f32 v[176:177], v[176:177], v[236:237] op_sel_hi:[1,0]
	v_pk_mul_f32 v[178:179], v[178:179], v[236:237] op_sel_hi:[1,0]
	v_pk_mul_f32 v[180:181], v[180:181], v[236:237] op_sel_hi:[1,0]
	v_pk_mul_f32 v[182:183], v[182:183], v[236:237] op_sel_hi:[1,0]
	v_pk_mul_f32 v[184:185], v[184:185], v[236:237] op_sel_hi:[1,0]
	v_pk_mul_f32 v[186:187], v[186:187], v[236:237] op_sel_hi:[1,0]
	v_pk_mul_f32 v[188:189], v[188:189], v[236:237] op_sel_hi:[1,0]
	v_pk_mul_f32 v[190:191], v[190:191], v[236:237] op_sel_hi:[1,0]
	v_cvt_pk_bf16_f32 v32, v32, v33
	v_cvt_pk_bf16_f32 v33, v34, v35
	v_cvt_pk_bf16_f32 v34, v36, v37
	v_cvt_pk_bf16_f32 v35, v38, v39
	v_cvt_pk_bf16_f32 v36, v40, v41
	v_cvt_pk_bf16_f32 v37, v42, v43
	v_cvt_pk_bf16_f32 v38, v44, v45
	v_cvt_pk_bf16_f32 v39, v46, v47
	v_cvt_pk_bf16_f32 v48, v48, v49
	v_cvt_pk_bf16_f32 v49, v50, v51
	v_cvt_pk_bf16_f32 v50, v52, v53
	v_cvt_pk_bf16_f32 v51, v54, v55
	v_cvt_pk_bf16_f32 v52, v56, v57
	v_cvt_pk_bf16_f32 v53, v58, v59
	v_cvt_pk_bf16_f32 v54, v60, v61
	v_cvt_pk_bf16_f32 v55, v62, v63
	s_nop 1
	v_mfma_f32_32x32x16_bf16 v[128:143], a[96:99], v[32:35], v[128:143]
	v_mfma_f32_32x32x16_bf16 v[128:143], a[100:103], v[36:39], v[128:143]
	v_mfma_f32_32x32x16_bf16 v[144:159], a[104:107], v[32:35], v[144:159]
	v_mfma_f32_32x32x16_bf16 v[144:159], a[108:111], v[36:39], v[144:159]
	v_mfma_f32_32x32x16_bf16 v[160:175], a[112:115], v[32:35], v[160:175]
	v_mfma_f32_32x32x16_bf16 v[160:175], a[116:119], v[36:39], v[160:175]
	v_mfma_f32_32x32x16_bf16 v[176:191], a[120:123], v[32:35], v[176:191]
	v_mfma_f32_32x32x16_bf16 v[176:191], a[124:127], v[36:39], v[176:191]
	v_mfma_f32_32x32x16_bf16 v[128:143], a[128:131], v[48:51], v[128:143]
	v_mfma_f32_32x32x16_bf16 v[128:143], a[132:135], v[52:55], v[128:143]
	v_mfma_f32_32x32x16_bf16 v[144:159], a[136:139], v[48:51], v[144:159]
	v_mfma_f32_32x32x16_bf16 v[144:159], a[140:143], v[52:55], v[144:159]
	v_mfma_f32_32x32x16_bf16 v[160:175], a[144:147], v[48:51], v[160:175]
	v_mfma_f32_32x32x16_bf16 v[160:175], a[148:151], v[52:55], v[160:175]
	v_mfma_f32_32x32x16_bf16 v[176:191], a[152:155], v[48:51], v[176:191]
	v_mfma_f32_32x32x16_bf16 v[176:191], a[156:159], v[52:55], v[176:191]
	s_branch .Lat_skip
.Lat_diag:
	s_waitcnt lgkmcnt(15)
	v_mfma_f32_32x32x16_bf16 v[192:207], a[32:35], a[0:3], 0
	s_waitcnt lgkmcnt(11)
	v_mfma_f32_32x32x16_bf16 v[208:223], a[48:51], a[0:3], 0
	s_waitcnt lgkmcnt(14)
	v_mfma_f32_32x32x16_bf16 v[192:207], a[36:39], a[4:7], v[192:207]
	s_waitcnt lgkmcnt(10)
	v_mfma_f32_32x32x16_bf16 v[208:223], a[52:55], a[4:7], v[208:223]
	s_waitcnt lgkmcnt(13)
	v_mfma_f32_32x32x16_bf16 v[192:207], a[40:43], a[8:11], v[192:207]
	s_waitcnt lgkmcnt(9)
	v_mfma_f32_32x32x16_bf16 v[208:223], a[56:59], a[8:11], v[208:223]
	s_waitcnt lgkmcnt(12)
	v_mfma_f32_32x32x16_bf16 v[192:207], a[44:47], a[12:15], v[192:207]
	s_waitcnt lgkmcnt(8)
	v_mfma_f32_32x32x16_bf16 v[208:223], a[60:63], a[12:15], v[208:223]
	s_waitcnt lgkmcnt(7)
	v_mfma_f32_32x32x16_bf16 v[32:47], a[64:67], a[16:19], 0
	s_waitcnt lgkmcnt(3)
	v_mfma_f32_32x32x16_bf16 v[48:63], a[80:83], a[16:19], 0
	s_waitcnt lgkmcnt(6)
	v_mfma_f32_32x32x16_bf16 v[32:47], a[68:71], a[20:23], v[32:47]
	s_waitcnt lgkmcnt(2)
	v_mfma_f32_32x32x16_bf16 v[48:63], a[84:87], a[20:23], v[48:63]
	ds_read2_b64 a[96:99], v7 offset0:0 offset1:2
	ds_read2_b64 a[100:103], v7 offset0:4 offset1:6
	ds_read2_b64 a[128:131], v7 offset0:8 offset1:10
	ds_read2_b64 a[132:135], v7 offset0:12 offset1:14
	v_add_u32_e32 v28, 0x1200, v7
	ds_read2_b64 a[104:107], v28 offset0:0 offset1:2
	ds_read2_b64 a[108:111], v28 offset0:4 offset1:6
	ds_read2_b64 a[136:139], v28 offset0:8 offset1:10
	ds_read2_b64 a[140:143], v28 offset0:12 offset1:14
	v_add_u32_e32 v28, 0x2400, v7
	ds_read2_b64 a[112:115], v28 offset0:0 offset1:2
	ds_read2_b64 a[116:119], v28 offset0:4 offset1:6
	ds_read2_b64 a[144:147], v28 offset0:8 offset1:10
	ds_read2_b64 a[148:151], v28 offset0:12 offset1:14
	v_add_u32_e32 v28, 0x3600, v7
	ds_read2_b64 a[120:123], v28 offset0:0 offset1:2
	ds_read2_b64 a[124:127], v28 offset0:4 offset1:6
	ds_read2_b64 a[152:155], v28 offset0:8 offset1:10
	ds_read2_b64 a[156:159], v28 offset0:12 offset1:14
	s_waitcnt lgkmcnt(15)
	v_mfma_f32_32x32x16_bf16 v[32:47], a[72:75], a[24:27], v[32:47]
	v_cmp_gt_i32_e64 s[0:1], 0, v25
	v_cmp_gt_i32_e64 s[4:5], 1, v25
	v_cmp_gt_i32_e64 s[10:11], 2, v25
	v_cmp_gt_i32_e64 s[20:21], 3, v25
	v_cndmask_b32_e64 v192, v192, v27, s[0:1]
	v_cndmask_b32_e64 v193, v193, v27, s[4:5]
	v_cndmask_b32_e64 v194, v194, v27, s[10:11]
	v_cndmask_b32_e64 v195, v195, v27, s[20:21]
	s_waitcnt lgkmcnt(15)
	v_mfma_f32_32x32x16_bf16 v[48:63], a[88:91], a[24:27], v[48:63]
	v_cmp_gt_i32_e64 s[0:1], 8, v25
	v_cmp_gt_i32_e64 s[4:5], 9, v25
	v_cmp_gt_i32_e64 s[10:11], 10, v25
	v_cmp_gt_i32_e64 s[20:21], 11, v25
	v_cndmask_b32_e64 v196, v196, v27, s[0:1]
	v_cndmask_b32_e64 v197, v197, v27, s[4:5]
	v_cndmask_b32_e64 v198, v198, v27, s[10:11]
	v_cndmask_b32_e64 v199, v199, v27, s[20:21]
	s_waitcnt lgkmcnt(15)
	v_mfma_f32_32x32x16_bf16 v[32:47], a[76:79], a[28:31], v[32:47]
	v_cmp_gt_i32_e64 s[0:1], 16, v25
	v_cmp_gt_i32_e64 s[4:5], 17, v25
	v_cmp_gt_i32_e64 s[10:11], 18, v25
	v_cmp_gt_i32_e64 s[20:21], 19, v25
	v_cndmask_b32_e64 v200, v200, v27, s[0:1]
	v_cndmask_b32_e64 v201, v201, v27, s[4:5]
	v_cndmask_b32_e64 v202, v202, v27, s[10:11]
	v_cndmask_b32_e64 v203, v203, v27, s[20:21]
	s_waitcnt lgkmcnt(15)
	v_mfma_f32_32x32x16_bf16 v[48:63], a[92:95], a[28:31], v[48:63]
	v_cmp_gt_i32_e64 s[0:1], 24, v25
	v_cmp_gt_i32_e64 s[4:5], 25, v25
	v_cmp_gt_i32_e64 s[10:11], 26, v25
	v_cmp_gt_i32_e64 s[20:21], 27, v25
	v_cndmask_b32_e64 v204, v204, v27, s[0:1]
	v_cndmask_b32_e64 v205, v205, v27, s[4:5]
	v_cndmask_b32_e64 v206, v206, v27, s[10:11]
	v_cndmask_b32_e64 v207, v207, v27, s[20:21]
	v_cmp_gt_i32_e64 s[0:1], 32, v25
	v_cmp_gt_i32_e64 s[4:5], 33, v25
	v_cmp_gt_i32_e64 s[10:11], 34, v25
	v_cmp_gt_i32_e64 s[20:21], 35, v25
	v_cndmask_b32_e64 v208, v208, v27, s[0:1]
	v_cndmask_b32_e64 v209, v209, v27, s[4:5]
	v_cndmask_b32_e64 v210, v210, v27, s[10:11]
	v_cndmask_b32_e64 v211, v211, v27, s[20:21]
	v_cmp_gt_i32_e64 s[0:1], 40, v25
	v_cmp_gt_i32_e64 s[4:5], 41, v25
	v_cmp_gt_i32_e64 s[10:11], 42, v25
	v_cmp_gt_i32_e64 s[20:21], 43, v25
	v_cndmask_b32_e64 v212, v212, v27, s[0:1]
	v_cndmask_b32_e64 v213, v213, v27, s[4:5]
	v_cndmask_b32_e64 v214, v214, v27, s[10:11]
	v_cndmask_b32_e64 v215, v215, v27, s[20:21]
	v_cmp_gt_i32_e64 s[0:1], 48, v25
	v_cmp_gt_i32_e64 s[4:5], 49, v25
	v_cmp_gt_i32_e64 s[10:11], 50, v25
	v_cmp_gt_i32_e64 s[20:21], 51, v25
	v_cndmask_b32_e64 v216, v216, v27, s[0:1]
	v_cndmask_b32_e64 v217, v217, v27, s[4:5]
	v_cndmask_b32_e64 v218, v218, v27, s[10:11]
	v_cndmask_b32_e64 v219, v219, v27, s[20:21]
	v_cmp_gt_i32_e64 s[0:1], 56, v25
	v_cmp_gt_i32_e64 s[4:5], 57, v25
	v_cmp_gt_i32_e64 s[10:11], 58, v25
	v_cmp_gt_i32_e64 s[20:21], 59, v25
	v_cndmask_b32_e64 v220, v220, v27, s[0:1]
	v_cndmask_b32_e64 v221, v221, v27, s[4:5]
	v_cndmask_b32_e64 v222, v222, v27, s[10:11]
	v_cndmask_b32_e64 v223, v223, v27, s[20:21]
	v_max3_f32 v224, v192, v193, v194
	v_max3_f32 v224, v224, v195, v196
	v_max3_f32 v224, v224, v197, v198
	v_max3_f32 v224, v224, v199, v200
	v_max3_f32 v224, v224, v201, v202
	v_max3_f32 v224, v224, v203, v204
	v_max3_f32 v224, v224, v205, v206
	v_max3_f32 v224, v224, v207, v208
	v_max3_f32 v224, v224, v209, v210
	v_max3_f32 v224, v224, v211, v212
	v_max3_f32 v224, v224, v213, v214
	v_max3_f32 v224, v224, v215, v216
	v_max3_f32 v224, v224, v217, v218
	v_max3_f32 v224, v224, v219, v220
	v_max3_f32 v224, v224, v221, v222
	v_max_f32_e32 v224, v224, v223
	ds_bpermute_b32 v225, v26, v224
	s_waitcnt lgkmcnt(0)
	v_max3_f32 v226, v224, v225, v20
	v_sub_f32_e32 v228, v20, v226
	v_exp_f32_e32 v228, v228
	v_mov_b32_e32 v20, v226
	v_sub_f32_e32 v192, v192, v226
	v_sub_f32_e32 v193, v193, v226
	v_sub_f32_e32 v194, v194, v226
	v_sub_f32_e32 v195, v195, v226
	v_sub_f32_e32 v196, v196, v226
	v_sub_f32_e32 v197, v197, v226
	v_sub_f32_e32 v198, v198, v226
	v_sub_f32_e32 v199, v199, v226
	v_sub_f32_e32 v200, v200, v226
	v_sub_f32_e32 v201, v201, v226
	v_sub_f32_e32 v202, v202, v226
	v_sub_f32_e32 v203, v203, v226
	v_sub_f32_e32 v204, v204, v226
	v_sub_f32_e32 v205, v205, v226
	v_sub_f32_e32 v206, v206, v226
	v_sub_f32_e32 v207, v207, v226
	v_sub_f32_e32 v208, v208, v226
	v_sub_f32_e32 v209, v209, v226
	v_sub_f32_e32 v210, v210, v226
	v_sub_f32_e32 v211, v211, v226
	v_sub_f32_e32 v212, v212, v226
	v_sub_f32_e32 v213, v213, v226
	v_sub_f32_e32 v214, v214, v226
	v_sub_f32_e32 v215, v215, v226
	v_sub_f32_e32 v216, v216, v226
	v_sub_f32_e32 v217, v217, v226
	v_sub_f32_e32 v218, v218, v226
	v_sub_f32_e32 v219, v219, v226
	v_sub_f32_e32 v220, v220, v226
	v_sub_f32_e32 v221, v221, v226
	v_sub_f32_e32 v222, v222, v226
	v_sub_f32_e32 v223, v223, v226
	v_exp_f32_e32 v192, v192
	v_exp_f32_e32 v193, v193
	v_exp_f32_e32 v194, v194
	v_exp_f32_e32 v195, v195
	v_exp_f32_e32 v196, v196
	v_exp_f32_e32 v197, v197
	v_exp_f32_e32 v198, v198
	v_exp_f32_e32 v199, v199
	v_exp_f32_e32 v200, v200
	v_exp_f32_e32 v201, v201
	v_exp_f32_e32 v202, v202
	v_exp_f32_e32 v203, v203
	v_exp_f32_e32 v204, v204
	v_exp_f32_e32 v205, v205
	v_exp_f32_e32 v206, v206
	v_exp_f32_e32 v207, v207
	v_exp_f32_e32 v208, v208
	v_exp_f32_e32 v209, v209
	v_exp_f32_e32 v210, v210
	v_exp_f32_e32 v211, v211
	v_exp_f32_e32 v212, v212
	v_exp_f32_e32 v213, v213
	v_exp_f32_e32 v214, v214
	v_exp_f32_e32 v215, v215
	v_exp_f32_e32 v216, v216
	v_exp_f32_e32 v217, v217
	v_exp_f32_e32 v218, v218
	v_exp_f32_e32 v219, v219
	v_exp_f32_e32 v220, v220
	v_exp_f32_e32 v221, v221
	v_exp_f32_e32 v222, v222
	v_exp_f32_e32 v223, v223
	v_mul_f32_e32 v22, v22, v228
	v_add_f32_e32 v230, v192, v193
	v_add_f32_e32 v230, v230, v194
	v_add_f32_e32 v230, v230, v195
	v_add_f32_e32 v230, v230, v196
	v_add_f32_e32 v230, v230, v197
	v_add_f32_e32 v230, v230, v198
	v_add_f32_e32 v230, v230, v199
	v_add_f32_e32 v230, v230, v200
	v_add_f32_e32 v230, v230, v201
	v_add_f32_e32 v230, v230, v202
	v_add_f32_e32 v230, v230, v203
	v_add_f32_e32 v230, v230, v204
	v_add_f32_e32 v230, v230, v205
	v_add_f32_e32 v230, v230, v206
	v_add_f32_e32 v230, v230, v207
	v_add_f32_e32 v230, v230, v208
	v_add_f32_e32 v230, v230, v209
	v_add_f32_e32 v230, v230, v210
	v_add_f32_e32 v230, v230, v211
	v_add_f32_e32 v230, v230, v212
	v_add_f32_e32 v230, v230, v213
	v_add_f32_e32 v230, v230, v214
	v_add_f32_e32 v230, v230, v215
	v_add_f32_e32 v230, v230, v216
	v_add_f32_e32 v230, v230, v217
	v_add_f32_e32 v230, v230, v218
	v_add_f32_e32 v230, v230, v219
	v_add_f32_e32 v230, v230, v220
	v_add_f32_e32 v230, v230, v221
	v_add_f32_e32 v230, v230, v222
	v_add_f32_e32 v230, v230, v223
	v_add_f32_e32 v22, v22, v230
	v_pk_mul_f32 v[64:65], v[64:65], v[228:229] op_sel_hi:[1,0]
	v_pk_mul_f32 v[66:67], v[66:67], v[228:229] op_sel_hi:[1,0]
	v_pk_mul_f32 v[68:69], v[68:69], v[228:229] op_sel_hi:[1,0]
	v_pk_mul_f32 v[70:71], v[70:71], v[228:229] op_sel_hi:[1,0]
	v_pk_mul_f32 v[72:73], v[72:73], v[228:229] op_sel_hi:[1,0]
	v_pk_mul_f32 v[74:75], v[74:75], v[228:229] op_sel_hi:[1,0]
	v_pk_mul_f32 v[76:77], v[76:77], v[228:229] op_sel_hi:[1,0]
	v_pk_mul_f32 v[78:79], v[78:79], v[228:229] op_sel_hi:[1,0]
	v_pk_mul_f32 v[80:81], v[80:81], v[228:229] op_sel_hi:[1,0]
	v_pk_mul_f32 v[82:83], v[82:83], v[228:229] op_sel_hi:[1,0]
	v_pk_mul_f32 v[84:85], v[84:85], v[228:229] op_sel_hi:[1,0]
	v_pk_mul_f32 v[86:87], v[86:87], v[228:229] op_sel_hi:[1,0]
	v_pk_mul_f32 v[88:89], v[88:89], v[228:229] op_sel_hi:[1,0]
	v_pk_mul_f32 v[90:91], v[90:91], v[228:229] op_sel_hi:[1,0]
	v_pk_mul_f32 v[92:93], v[92:93], v[228:229] op_sel_hi:[1,0]
	v_pk_mul_f32 v[94:95], v[94:95], v[228:229] op_sel_hi:[1,0]
	v_pk_mul_f32 v[96:97], v[96:97], v[228:229] op_sel_hi:[1,0]
	v_pk_mul_f32 v[98:99], v[98:99], v[228:229] op_sel_hi:[1,0]
	v_pk_mul_f32 v[100:101], v[100:101], v[228:229] op_sel_hi:[1,0]
	v_pk_mul_f32 v[102:103], v[102:103], v[228:229] op_sel_hi:[1,0]
	v_pk_mul_f32 v[104:105], v[104:105], v[228:229] op_sel_hi:[1,0]
	v_pk_mul_f32 v[106:107], v[106:107], v[228:229] op_sel_hi:[1,0]
	v_pk_mul_f32 v[108:109], v[108:109], v[228:229] op_sel_hi:[1,0]
	v_pk_mul_f32 v[110:111], v[110:111], v[228:229] op_sel_hi:[1,0]
	v_pk_mul_f32 v[112:113], v[112:113], v[228:229] op_sel_hi:[1,0]
	v_pk_mul_f32 v[114:115], v[114:115], v[228:229] op_sel_hi:[1,0]
	v_pk_mul_f32 v[116:117], v[116:117], v[228:229] op_sel_hi:[1,0]
	v_pk_mul_f32 v[118:119], v[118:119], v[228:229] op_sel_hi:[1,0]
	v_pk_mul_f32 v[120:121], v[120:121], v[228:229] op_sel_hi:[1,0]
	v_pk_mul_f32 v[122:123], v[122:123], v[228:229] op_sel_hi:[1,0]
	v_pk_mul_f32 v[124:125], v[124:125], v[228:229] op_sel_hi:[1,0]
	v_pk_mul_f32 v[126:127], v[126:127], v[228:229] op_sel_hi:[1,0]
	v_cvt_pk_bf16_f32 v192, v192, v193
	v_cvt_pk_bf16_f32 v193, v194, v195
	v_cvt_pk_bf16_f32 v194, v196, v197
	v_cvt_pk_bf16_f32 v195, v198, v199
	v_cvt_pk_bf16_f32 v196, v200, v201
	v_cvt_pk_bf16_f32 v197, v202, v203
	v_cvt_pk_bf16_f32 v198, v204, v205
	v_cvt_pk_bf16_f32 v199, v206, v207
	v_cvt_pk_bf16_f32 v208, v208, v209
	v_cvt_pk_bf16_f32 v209, v210, v211
	v_cvt_pk_bf16_f32 v210, v212, v213
	v_cvt_pk_bf16_f32 v211, v214, v215
	v_cvt_pk_bf16_f32 v212, v216, v217
	v_cvt_pk_bf16_f32 v213, v218, v219
	v_cvt_pk_bf16_f32 v214, v220, v221
	v_cvt_pk_bf16_f32 v215, v222, v223
	s_nop 1
	v_mfma_f32_32x32x16_bf16 v[64:79], a[96:99], v[192:195], v[64:79]
	v_cmp_gt_i32_e64 s[0:1], 0, v25
	v_cmp_gt_i32_e64 s[4:5], 1, v25
	v_cmp_gt_i32_e64 s[10:11], 2, v25
	v_cmp_gt_i32_e64 s[20:21], 3, v25
	v_cndmask_b32_e64 v32, v32, v27, s[0:1]
	v_cndmask_b32_e64 v33, v33, v27, s[4:5]
	v_cndmask_b32_e64 v34, v34, v27, s[10:11]
	v_cndmask_b32_e64 v35, v35, v27, s[20:21]
	v_mfma_f32_32x32x16_bf16 v[64:79], a[100:103], v[196:199], v[64:79]
	v_cmp_gt_i32_e64 s[0:1], 8, v25
	v_cmp_gt_i32_e64 s[4:5], 9, v25
	v_cmp_gt_i32_e64 s[10:11], 10, v25
	v_cmp_gt_i32_e64 s[20:21], 11, v25
	v_cndmask_b32_e64 v36, v36, v27, s[0:1]
	v_cndmask_b32_e64 v37, v37, v27, s[4:5]
	v_cndmask_b32_e64 v38, v38, v27, s[10:11]
	v_cndmask_b32_e64 v39, v39, v27, s[20:21]
	v_mfma_f32_32x32x16_bf16 v[80:95], a[104:107], v[192:195], v[80:95]
	v_cmp_gt_i32_e64 s[0:1], 16, v25
	v_cmp_gt_i32_e64 s[4:5], 17, v25
	v_cmp_gt_i32_e64 s[10:11], 18, v25
	v_cmp_gt_i32_e64 s[20:21], 19, v25
	v_cndmask_b32_e64 v40, v40, v27, s[0:1]
	v_cndmask_b32_e64 v41, v41, v27, s[4:5]
	v_cndmask_b32_e64 v42, v42, v27, s[10:11]
	v_cndmask_b32_e64 v43, v43, v27, s[20:21]
	v_mfma_f32_32x32x16_bf16 v[80:95], a[108:111], v[196:199], v[80:95]
	v_cmp_gt_i32_e64 s[0:1], 24, v25
	v_cmp_gt_i32_e64 s[4:5], 25, v25
	v_cmp_gt_i32_e64 s[10:11], 26, v25
	v_cmp_gt_i32_e64 s[20:21], 27, v25
	v_cndmask_b32_e64 v44, v44, v27, s[0:1]
	v_cndmask_b32_e64 v45, v45, v27, s[4:5]
	v_cndmask_b32_e64 v46, v46, v27, s[10:11]
	v_cndmask_b32_e64 v47, v47, v27, s[20:21]
	v_mfma_f32_32x32x16_bf16 v[96:111], a[112:115], v[192:195], v[96:111]
	v_cmp_gt_i32_e64 s[0:1], 32, v25
	v_cmp_gt_i32_e64 s[4:5], 33, v25
	v_cmp_gt_i32_e64 s[10:11], 34, v25
	v_cmp_gt_i32_e64 s[20:21], 35, v25
	v_cndmask_b32_e64 v48, v48, v27, s[0:1]
	v_cndmask_b32_e64 v49, v49, v27, s[4:5]
	v_cndmask_b32_e64 v50, v50, v27, s[10:11]
	v_cndmask_b32_e64 v51, v51, v27, s[20:21]
	v_mfma_f32_32x32x16_bf16 v[96:111], a[116:119], v[196:199], v[96:111]
	v_cmp_gt_i32_e64 s[0:1], 40, v25
	v_cmp_gt_i32_e64 s[4:5], 41, v25
	v_cmp_gt_i32_e64 s[10:11], 42, v25
	v_cmp_gt_i32_e64 s[20:21], 43, v25
	v_cndmask_b32_e64 v52, v52, v27, s[0:1]
	v_cndmask_b32_e64 v53, v53, v27, s[4:5]
	v_cndmask_b32_e64 v54, v54, v27, s[10:11]
	v_cndmask_b32_e64 v55, v55, v27, s[20:21]
	v_mfma_f32_32x32x16_bf16 v[112:127], a[120:123], v[192:195], v[112:127]
	v_cmp_gt_i32_e64 s[0:1], 48, v25
	v_cmp_gt_i32_e64 s[4:5], 49, v25
	v_cmp_gt_i32_e64 s[10:11], 50, v25
	v_cmp_gt_i32_e64 s[20:21], 51, v25
	v_cndmask_b32_e64 v56, v56, v27, s[0:1]
	v_cndmask_b32_e64 v57, v57, v27, s[4:5]
	v_cndmask_b32_e64 v58, v58, v27, s[10:11]
	v_cndmask_b32_e64 v59, v59, v27, s[20:21]
	v_mfma_f32_32x32x16_bf16 v[112:127], a[124:127], v[196:199], v[112:127]
	v_cmp_gt_i32_e64 s[0:1], 56, v25
	v_cmp_gt_i32_e64 s[4:5], 57, v25
	v_cmp_gt_i32_e64 s[10:11], 58, v25
	v_cmp_gt_i32_e64 s[20:21], 59, v25
	v_cndmask_b32_e64 v60, v60, v27, s[0:1]
	v_cndmask_b32_e64 v61, v61, v27, s[4:5]
	v_cndmask_b32_e64 v62, v62, v27, s[10:11]
	v_cndmask_b32_e64 v63, v63, v27, s[20:21]
	v_mfma_f32_32x32x16_bf16 v[64:79], a[128:131], v[208:211], v[64:79]
	v_max3_f32 v232, v32, v33, v34
	v_max3_f32 v232, v232, v35, v36
	v_max3_f32 v232, v232, v37, v38
	v_max3_f32 v232, v232, v39, v40
	v_max3_f32 v232, v232, v41, v42
	v_max3_f32 v232, v232, v43, v44
	v_max3_f32 v232, v232, v45, v46
	v_max3_f32 v232, v232, v47, v48
	v_mfma_f32_32x32x16_bf16 v[64:79], a[132:135], v[212:215], v[64:79]
	v_max3_f32 v232, v232, v49, v50
	v_max3_f32 v232, v232, v51, v52
	v_max3_f32 v232, v232, v53, v54
	v_max3_f32 v232, v232, v55, v56
	v_max3_f32 v232, v232, v57, v58
	v_max3_f32 v232, v232, v59, v60
	v_max3_f32 v232, v232, v61, v62
	v_max_f32_e32 v232, v232, v63
	v_mfma_f32_32x32x16_bf16 v[80:95], a[136:139], v[208:211], v[80:95]
	ds_bpermute_b32 v233, v26, v232
	s_waitcnt lgkmcnt(0)
	v_max3_f32 v234, v232, v233, v21
	v_sub_f32_e32 v236, v21, v234
	v_exp_f32_e32 v236, v236
	v_mov_b32_e32 v21, v234
	v_sub_f32_e32 v32, v32, v234
	v_sub_f32_e32 v33, v33, v234
	v_mfma_f32_32x32x16_bf16 v[80:95], a[140:143], v[212:215], v[80:95]
	v_sub_f32_e32 v34, v34, v234
	v_sub_f32_e32 v35, v35, v234
	v_sub_f32_e32 v36, v36, v234
	v_sub_f32_e32 v37, v37, v234
	v_sub_f32_e32 v38, v38, v234
	v_sub_f32_e32 v39, v39, v234
	v_sub_f32_e32 v40, v40, v234
	v_sub_f32_e32 v41, v41, v234
	v_mfma_f32_32x32x16_bf16 v[96:111], a[144:147], v[208:211], v[96:111]
	v_sub_f32_e32 v42, v42, v234
	v_sub_f32_e32 v43, v43, v234
	v_sub_f32_e32 v44, v44, v234
	v_sub_f32_e32 v45, v45, v234
	v_sub_f32_e32 v46, v46, v234
	v_sub_f32_e32 v47, v47, v234
	v_sub_f32_e32 v48, v48, v234
	v_sub_f32_e32 v49, v49, v234
	v_mfma_f32_32x32x16_bf16 v[96:111], a[148:151], v[212:215], v[96:111]
	v_sub_f32_e32 v50, v50, v234
	v_sub_f32_e32 v51, v51, v234
	v_sub_f32_e32 v52, v52, v234
	v_sub_f32_e32 v53, v53, v234
	v_sub_f32_e32 v54, v54, v234
	v_sub_f32_e32 v55, v55, v234
	v_sub_f32_e32 v56, v56, v234
	v_sub_f32_e32 v57, v57, v234
	v_mfma_f32_32x32x16_bf16 v[112:127], a[152:155], v[208:211], v[112:127]
	v_sub_f32_e32 v58, v58, v234
	v_sub_f32_e32 v59, v59, v234
	v_sub_f32_e32 v60, v60, v234
	v_sub_f32_e32 v61, v61, v234
	v_sub_f32_e32 v62, v62, v234
	v_sub_f32_e32 v63, v63, v234
	v_exp_f32_e32 v32, v32
	v_exp_f32_e32 v33, v33
	v_mfma_f32_32x32x16_bf16 v[112:127], a[156:159], v[212:215], v[112:127]
	v_exp_f32_e32 v34, v34
	v_exp_f32_e32 v35, v35
	v_exp_f32_e32 v36, v36
	v_exp_f32_e32 v37, v37
	v_exp_f32_e32 v38, v38
	v_exp_f32_e32 v39, v39
	v_exp_f32_e32 v40, v40
	v_exp_f32_e32 v41, v41
	v_exp_f32_e32 v42, v42
	v_exp_f32_e32 v43, v43
	v_exp_f32_e32 v44, v44
	v_exp_f32_e32 v45, v45
	v_exp_f32_e32 v46, v46
	v_exp_f32_e32 v47, v47
	v_exp_f32_e32 v48, v48
	v_exp_f32_e32 v49, v49
	v_exp_f32_e32 v50, v50
	v_exp_f32_e32 v51, v51
	v_exp_f32_e32 v52, v52
	v_exp_f32_e32 v53, v53
	v_exp_f32_e32 v54, v54
	v_exp_f32_e32 v55, v55
	v_exp_f32_e32 v56, v56
	v_exp_f32_e32 v57, v57
	v_exp_f32_e32 v58, v58
	v_exp_f32_e32 v59, v59
	v_exp_f32_e32 v60, v60
	v_exp_f32_e32 v61, v61
	v_exp_f32_e32 v62, v62
	v_exp_f32_e32 v63, v63
	v_mul_f32_e32 v23, v23, v236
	v_add_f32_e32 v238, v32, v33
	v_add_f32_e32 v238, v238, v34
	v_add_f32_e32 v238, v238, v35
	v_add_f32_e32 v238, v238, v36
	v_add_f32_e32 v238, v238, v37
	v_add_f32_e32 v238, v238, v38
	v_add_f32_e32 v238, v238, v39
	v_add_f32_e32 v238, v238, v40
	v_add_f32_e32 v238, v238, v41
	v_add_f32_e32 v238, v238, v42
	v_add_f32_e32 v238, v238, v43
	v_add_f32_e32 v238, v238, v44
	v_add_f32_e32 v238, v238, v45
	v_add_f32_e32 v238, v238, v46
	v_add_f32_e32 v238, v238, v47
	v_add_f32_e32 v238, v238, v48
	v_add_f32_e32 v238, v238, v49
	v_add_f32_e32 v238, v238, v50
	v_add_f32_e32 v238, v238, v51
	v_add_f32_e32 v238, v238, v52
	v_add_f32_e32 v238, v238, v53
	v_add_f32_e32 v238, v238, v54
	v_add_f32_e32 v238, v238, v55
	v_add_f32_e32 v238, v238, v56
	v_add_f32_e32 v238, v238, v57
	v_add_f32_e32 v238, v238, v58
	v_add_f32_e32 v238, v238, v59
	v_add_f32_e32 v238, v238, v60
	v_add_f32_e32 v238, v238, v61
	v_add_f32_e32 v238, v238, v62
	v_add_f32_e32 v238, v238, v63
	v_add_f32_e32 v23, v23, v238
	v_pk_mul_f32 v[128:129], v[128:129], v[236:237] op_sel_hi:[1,0]
	v_pk_mul_f32 v[130:131], v[130:131], v[236:237] op_sel_hi:[1,0]
	v_pk_mul_f32 v[132:133], v[132:133], v[236:237] op_sel_hi:[1,0]
	v_pk_mul_f32 v[134:135], v[134:135], v[236:237] op_sel_hi:[1,0]
	v_pk_mul_f32 v[136:137], v[136:137], v[236:237] op_sel_hi:[1,0]
	v_pk_mul_f32 v[138:139], v[138:139], v[236:237] op_sel_hi:[1,0]
	v_pk_mul_f32 v[140:141], v[140:141], v[236:237] op_sel_hi:[1,0]
	v_pk_mul_f32 v[142:143], v[142:143], v[236:237] op_sel_hi:[1,0]
	v_pk_mul_f32 v[144:145], v[144:145], v[236:237] op_sel_hi:[1,0]
	v_pk_mul_f32 v[146:147], v[146:147], v[236:237] op_sel_hi:[1,0]
	v_pk_mul_f32 v[148:149], v[148:149], v[236:237] op_sel_hi:[1,0]
	v_pk_mul_f32 v[150:151], v[150:151], v[236:237] op_sel_hi:[1,0]
	v_pk_mul_f32 v[152:153], v[152:153], v[236:237] op_sel_hi:[1,0]
	v_pk_mul_f32 v[154:155], v[154:155], v[236:237] op_sel_hi:[1,0]
	v_pk_mul_f32 v[156:157], v[156:157], v[236:237] op_sel_hi:[1,0]
	v_pk_mul_f32 v[158:159], v[158:159], v[236:237] op_sel_hi:[1,0]
	v_pk_mul_f32 v[160:161], v[160:161], v[236:237] op_sel_hi:[1,0]
	v_pk_mul_f32 v[162:163], v[162:163], v[236:237] op_sel_hi:[1,0]
	v_pk_mul_f32 v[164:165], v[164:165], v[236:237] op_sel_hi:[1,0]
	v_pk_mul_f32 v[166:167], v[166:167], v[236:237] op_sel_hi:[1,0]
	v_pk_mul_f32 v[168:169], v[168:169], v[236:237] op_sel_hi:[1,0]
	v_pk_mul_f32 v[170:171], v[170:171], v[236:237] op_sel_hi:[1,0]
	v_pk_mul_f32 v[172:173], v[172:173], v[236:237] op_sel_hi:[1,0]
	v_pk_mul_f32 v[174:175], v[174:175], v[236:237] op_sel_hi:[1,0]
	v_pk_mul_f32 v[176:177], v[176:177], v[236:237] op_sel_hi:[1,0]
	v_pk_mul_f32 v[178:179], v[178:179], v[236:237] op_sel_hi:[1,0]
	v_pk_mul_f32 v[180:181], v[180:181], v[236:237] op_sel_hi:[1,0]
	v_pk_mul_f32 v[182:183], v[182:183], v[236:237] op_sel_hi:[1,0]
	v_pk_mul_f32 v[184:185], v[184:185], v[236:237] op_sel_hi:[1,0]
	v_pk_mul_f32 v[186:187], v[186:187], v[236:237] op_sel_hi:[1,0]
	v_pk_mul_f32 v[188:189], v[188:189], v[236:237] op_sel_hi:[1,0]
	v_pk_mul_f32 v[190:191], v[190:191], v[236:237] op_sel_hi:[1,0]
	v_cvt_pk_bf16_f32 v32, v32, v33
	v_cvt_pk_bf16_f32 v33, v34, v35
	v_cvt_pk_bf16_f32 v34, v36, v37
	v_cvt_pk_bf16_f32 v35, v38, v39
	v_cvt_pk_bf16_f32 v36, v40, v41
	v_cvt_pk_bf16_f32 v37, v42, v43
	v_cvt_pk_bf16_f32 v38, v44, v45
	v_cvt_pk_bf16_f32 v39, v46, v47
	v_cvt_pk_bf16_f32 v48, v48, v49
	v_cvt_pk_bf16_f32 v49, v50, v51
	v_cvt_pk_bf16_f32 v50, v52, v53
	v_cvt_pk_bf16_f32 v51, v54, v55
	v_cvt_pk_bf16_f32 v52, v56, v57
	v_cvt_pk_bf16_f32 v53, v58, v59
	v_cvt_pk_bf16_f32 v54, v60, v61
	v_cvt_pk_bf16_f32 v55, v62, v63
	s_nop 1
	v_mfma_f32_32x32x16_bf16 v[128:143], a[96:99], v[32:35], v[128:143]
	v_mfma_f32_32x32x16_bf16 v[128:143], a[100:103], v[36:39], v[128:143]
	v_mfma_f32_32x32x16_bf16 v[144:159], a[104:107], v[32:35], v[144:159]
	v_mfma_f32_32x32x16_bf16 v[144:159], a[108:111], v[36:39], v[144:159]
	v_mfma_f32_32x32x16_bf16 v[160:175], a[112:115], v[32:35], v[160:175]
	v_mfma_f32_32x32x16_bf16 v[160:175], a[116:119], v[36:39], v[160:175]
	v_mfma_f32_32x32x16_bf16 v[176:191], a[120:123], v[32:35], v[176:191]
	v_mfma_f32_32x32x16_bf16 v[176:191], a[124:127], v[36:39], v[176:191]
	v_mfma_f32_32x32x16_bf16 v[128:143], a[128:131], v[48:51], v[128:143]
	v_mfma_f32_32x32x16_bf16 v[128:143], a[132:135], v[52:55], v[128:143]
	v_mfma_f32_32x32x16_bf16 v[144:159], a[136:139], v[48:51], v[144:159]
	v_mfma_f32_32x32x16_bf16 v[144:159], a[140:143], v[52:55], v[144:159]
	v_mfma_f32_32x32x16_bf16 v[160:175], a[144:147], v[48:51], v[160:175]
	v_mfma_f32_32x32x16_bf16 v[160:175], a[148:151], v[52:55], v[160:175]
	v_mfma_f32_32x32x16_bf16 v[176:191], a[152:155], v[48:51], v[176:191]
	v_mfma_f32_32x32x16_bf16 v[176:191], a[156:159], v[52:55], v[176:191]
